# v40 with the GU epilogue un-aligned between the two wave halves (alignment barriers removed, one re-align barrier at phase end)
# baseline (speedup 1.0000x reference)
.LBB0_532:
	s_add_u32 s6, s8, 0xfff80080
	s_addc_u32 s7, s9, -1
	s_add_i32 s29, 0, 0x10000
	s_cmp_eq_u32 s28, 28
	s_cselect_b32 s17, s13, s7
	s_cselect_b32 s16, s12, s6
	s_cselect_b32 s7, s15, s27
	s_cselect_b32 s6, s14, s26
	s_add_i32 s53, 0, 0x14000
	ds_read_b128 v[138:141], v240
	ds_read_b128 v[142:145], v240 offset:1024
	ds_read_b128 v[148:151], v240 offset:2048
	ds_read_b128 v[152:155], v240 offset:3072
	ds_read_b128 v[156:159], v240 offset:16384
	ds_read_b128 v[160:163], v240 offset:17408
	ds_read_b128 v[164:167], v240 offset:18432
	ds_read_b128 v[168:171], v240 offset:19456
	s_mov_b32 m0, s66
	ds_read_b128 v[172:175], v146
	ds_read_b128 v[176:179], v146 offset:1024
	ds_read_b128 v[180:183], v146 offset:2048
	ds_read_b128 v[184:187], v146 offset:3072
	ds_read_b128 v[188:191], v146 offset:4096
	ds_read_b128 v[192:195], v146 offset:5120
	ds_read_b128 v[196:199], v146 offset:6144
	ds_read_b128 v[200:203], v146 offset:7168
	global_load_lds_dwordx4 v2, s[8:9]
	s_mov_b32 m0, s67
	v_mov_b32_e32 v133, v3
	global_load_lds_dwordx4 v132, s[8:9]
	s_waitcnt vmcnt(8)
	s_waitcnt lgkmcnt(0)
	s_barrier
	s_setprio 1
	s_waitcnt lgkmcnt(0)
	v_mfma_f32_16x16x32_f16 v[4:7], v[138:141], v[172:175], v[4:7]
	v_mfma_f32_16x16x32_f16 v[4:7], v[142:145], v[176:179], v[4:7]
	v_mfma_f32_16x16x32_f16 v[8:11], v[152:155], v[176:179], v[8:11]
	v_mfma_f32_16x16x32_f16 v[8:11], v[148:151], v[172:175], v[8:11]
	v_mfma_f32_16x16x32_f16 v[16:19], v[148:151], v[180:183], v[16:19]
	v_mfma_f32_16x16x32_f16 v[16:19], v[152:155], v[184:187], v[16:19]
	v_mfma_f32_16x16x32_f16 v[12:15], v[142:145], v[184:187], v[12:15]
	v_mfma_f32_16x16x32_f16 v[12:15], v[138:141], v[180:183], v[12:15]
	v_mfma_f32_16x16x32_f16 v[20:23], v[138:141], v[188:191], v[20:23]
	v_mfma_f32_16x16x32_f16 v[20:23], v[142:145], v[192:195], v[20:23]
	v_mfma_f32_16x16x32_f16 v[24:27], v[152:155], v[192:195], v[24:27]
	v_mfma_f32_16x16x32_f16 v[24:27], v[148:151], v[188:191], v[24:27]
	v_mfma_f32_16x16x32_f16 v[32:35], v[148:151], v[196:199], v[32:35]
	v_mfma_f32_16x16x32_f16 v[32:35], v[152:155], v[200:203], v[32:35]
	v_mfma_f32_16x16x32_f16 v[28:31], v[142:145], v[200:203], v[28:31]
	v_mfma_f32_16x16x32_f16 v[28:31], v[138:141], v[196:199], v[28:31]
	s_setprio 0
	s_setprio 1
	v_mfma_f32_16x16x32_f16 v[36:39], v[156:159], v[172:175], v[36:39]
	v_mfma_f32_16x16x32_f16 v[36:39], v[160:163], v[176:179], v[36:39]
	v_mfma_f32_16x16x32_f16 v[40:43], v[168:171], v[176:179], v[40:43]
	v_mfma_f32_16x16x32_f16 v[40:43], v[164:167], v[172:175], v[40:43]
	v_mfma_f32_16x16x32_f16 v[48:51], v[164:167], v[180:183], v[48:51]
	v_mfma_f32_16x16x32_f16 v[48:51], v[168:171], v[184:187], v[48:51]
	v_mfma_f32_16x16x32_f16 v[44:47], v[160:163], v[184:187], v[44:47]
	v_mfma_f32_16x16x32_f16 v[44:47], v[156:159], v[180:183], v[44:47]
	v_mfma_f32_16x16x32_f16 v[52:55], v[156:159], v[188:191], v[52:55]
	v_mfma_f32_16x16x32_f16 v[52:55], v[160:163], v[192:195], v[52:55]
	v_mfma_f32_16x16x32_f16 v[56:59], v[168:171], v[192:195], v[56:59]
	v_mfma_f32_16x16x32_f16 v[56:59], v[164:167], v[188:191], v[56:59]
	v_mfma_f32_16x16x32_f16 v[64:67], v[164:167], v[196:199], v[64:67]
	v_mfma_f32_16x16x32_f16 v[64:67], v[168:171], v[200:203], v[64:67]
	s_setprio 2
	s_barrier
	v_mfma_f32_16x16x32_f16 v[60:63], v[160:163], v[200:203], v[60:63]
	v_mfma_f32_16x16x32_f16 v[60:63], v[156:159], v[196:199], v[60:63]
	s_setprio 0
	s_add_i32 s29, s29, s38
	s_mov_b32 m0, s29
	ds_read_b128 v[172:175], v146 offset:16384
	ds_read_b128 v[176:179], v146 offset:17408
	ds_read_b128 v[180:183], v146 offset:18432
	ds_read_b128 v[184:187], v146 offset:19456
	ds_read_b128 v[188:191], v146 offset:20480
	ds_read_b128 v[192:195], v146 offset:21504
	ds_read_b128 v[196:199], v146 offset:22528
	ds_read_b128 v[200:203], v146 offset:23552
	global_load_lds_dwordx4 v136, s[6:7]
	s_add_i32 m0, s29, 0x2000
	s_add_u32 s40, s6, 0x80000
	s_addc_u32 s41, s7, 0
	s_add_i32 s29, s53, s38
	global_load_lds_dwordx4 v134, s[6:7]
	s_mov_b32 m0, s29
	v_mov_b32_e32 v137, v3
	global_load_lds_dwordx4 v136, s[40:41]
	s_add_i32 m0, s29, 0x2000
	v_mov_b32_e32 v135, v3
	global_load_lds_dwordx4 v134, s[40:41]
	s_mov_b32 m0, s58
	s_nop 0
	global_load_lds_dwordx4 v2, s[16:17]
	s_mov_b32 m0, s59
	s_nop 0
	global_load_lds_dwordx4 v132, s[16:17]
	s_waitcnt vmcnt(8)
	s_waitcnt lgkmcnt(0)
	s_add_u32 s88, s6, s86
	s_addc_u32 s89, s7, s87
	s_add_u32 s90, s16, s86
	s_addc_u32 s91, s17, s87
	s_barrier
	s_setprio 1
	s_waitcnt lgkmcnt(0)
	v_mfma_f32_16x16x32_f16 v[68:71], v[138:141], v[172:175], v[68:71]
	v_mfma_f32_16x16x32_f16 v[68:71], v[142:145], v[176:179], v[68:71]
	v_mfma_f32_16x16x32_f16 v[72:75], v[152:155], v[176:179], v[72:75]
	v_mfma_f32_16x16x32_f16 v[72:75], v[148:151], v[172:175], v[72:75]
	v_mfma_f32_16x16x32_f16 v[80:83], v[148:151], v[180:183], v[80:83]
	v_mfma_f32_16x16x32_f16 v[80:83], v[152:155], v[184:187], v[80:83]
	v_mfma_f32_16x16x32_f16 v[76:79], v[142:145], v[184:187], v[76:79]
	v_mfma_f32_16x16x32_f16 v[76:79], v[138:141], v[180:183], v[76:79]
	v_mfma_f32_16x16x32_f16 v[84:87], v[138:141], v[188:191], v[84:87]
	v_mfma_f32_16x16x32_f16 v[84:87], v[142:145], v[192:195], v[84:87]
	v_mfma_f32_16x16x32_f16 v[88:91], v[152:155], v[192:195], v[88:91]
	v_mfma_f32_16x16x32_f16 v[88:91], v[148:151], v[188:191], v[88:91]
	v_mfma_f32_16x16x32_f16 v[96:99], v[148:151], v[196:199], v[96:99]
	v_mfma_f32_16x16x32_f16 v[96:99], v[152:155], v[200:203], v[96:99]
	v_mfma_f32_16x16x32_f16 v[92:95], v[142:145], v[200:203], v[92:95]
	v_mfma_f32_16x16x32_f16 v[92:95], v[138:141], v[196:199], v[92:95]
	s_setprio 0
	s_setprio 1
	v_mfma_f32_16x16x32_f16 v[100:103], v[156:159], v[172:175], v[100:103]
	v_mfma_f32_16x16x32_f16 v[100:103], v[160:163], v[176:179], v[100:103]
	v_mfma_f32_16x16x32_f16 v[104:107], v[168:171], v[176:179], v[104:107]
	v_mfma_f32_16x16x32_f16 v[104:107], v[164:167], v[172:175], v[104:107]
	v_mfma_f32_16x16x32_f16 v[112:115], v[164:167], v[180:183], v[112:115]
	v_mfma_f32_16x16x32_f16 v[112:115], v[168:171], v[184:187], v[112:115]
	v_mfma_f32_16x16x32_f16 v[108:111], v[160:163], v[184:187], v[108:111]
	v_mfma_f32_16x16x32_f16 v[108:111], v[156:159], v[180:183], v[108:111]
	v_mfma_f32_16x16x32_f16 v[116:119], v[156:159], v[188:191], v[116:119]
	v_mfma_f32_16x16x32_f16 v[116:119], v[160:163], v[192:195], v[116:119]
	v_mfma_f32_16x16x32_f16 v[120:123], v[168:171], v[192:195], v[120:123]
	v_mfma_f32_16x16x32_f16 v[120:123], v[164:167], v[188:191], v[120:123]
	v_mfma_f32_16x16x32_f16 v[128:131], v[164:167], v[196:199], v[128:131]
	v_mfma_f32_16x16x32_f16 v[128:131], v[168:171], v[200:203], v[128:131]
	s_setprio 2
	s_barrier
	v_mfma_f32_16x16x32_f16 v[124:127], v[160:163], v[200:203], v[124:127]
	v_mfma_f32_16x16x32_f16 v[124:127], v[156:159], v[196:199], v[124:127]
	s_setprio 0
	s_add_i32 s29, 0, 0x18000
	s_add_i32 s40, 0, 0x1c000
	ds_read_b128 v[138:141], v240 offset:32768
	ds_read_b128 v[142:145], v240 offset:33792
	ds_read_b128 v[148:151], v240 offset:34816
	ds_read_b128 v[152:155], v240 offset:35840
	ds_read_b128 v[156:159], v240 offset:49152
	ds_read_b128 v[160:163], v240 offset:50176
	ds_read_b128 v[164:167], v240 offset:51200
	ds_read_b128 v[168:171], v240 offset:52224
	s_add_u32 s16, s16, 0x80000
	s_addc_u32 s17, s17, 0
	s_mov_b32 m0, s60
	ds_read_b128 v[172:175], v146 offset:32768
	ds_read_b128 v[176:179], v146 offset:33792
	ds_read_b128 v[180:183], v146 offset:34816
	ds_read_b128 v[184:187], v146 offset:35840
	ds_read_b128 v[188:191], v146 offset:36864
	ds_read_b128 v[192:195], v146 offset:37888
	ds_read_b128 v[196:199], v146 offset:38912
	ds_read_b128 v[200:203], v146 offset:39936
	global_load_lds_dwordx4 v2, s[16:17]
	s_mov_b32 m0, s61
	s_nop 0
	global_load_lds_dwordx4 v132, s[16:17]
	s_waitcnt vmcnt(8)
	s_waitcnt lgkmcnt(0)
	s_barrier
	s_setprio 1
	s_waitcnt lgkmcnt(0)
	v_mfma_f32_16x16x32_f16 v[4:7], v[138:141], v[172:175], v[4:7]
	v_mfma_f32_16x16x32_f16 v[4:7], v[142:145], v[176:179], v[4:7]
	v_mfma_f32_16x16x32_f16 v[8:11], v[152:155], v[176:179], v[8:11]
	v_mfma_f32_16x16x32_f16 v[8:11], v[148:151], v[172:175], v[8:11]
	v_mfma_f32_16x16x32_f16 v[16:19], v[148:151], v[180:183], v[16:19]
	v_mfma_f32_16x16x32_f16 v[16:19], v[152:155], v[184:187], v[16:19]
	v_mfma_f32_16x16x32_f16 v[12:15], v[142:145], v[184:187], v[12:15]
	v_mfma_f32_16x16x32_f16 v[12:15], v[138:141], v[180:183], v[12:15]
	v_mfma_f32_16x16x32_f16 v[20:23], v[138:141], v[188:191], v[20:23]
	v_mfma_f32_16x16x32_f16 v[20:23], v[142:145], v[192:195], v[20:23]
	v_mfma_f32_16x16x32_f16 v[24:27], v[152:155], v[192:195], v[24:27]
	v_mfma_f32_16x16x32_f16 v[24:27], v[148:151], v[188:191], v[24:27]
	v_mfma_f32_16x16x32_f16 v[32:35], v[148:151], v[196:199], v[32:35]
	v_mfma_f32_16x16x32_f16 v[32:35], v[152:155], v[200:203], v[32:35]
	v_mfma_f32_16x16x32_f16 v[28:31], v[142:145], v[200:203], v[28:31]
	v_mfma_f32_16x16x32_f16 v[28:31], v[138:141], v[196:199], v[28:31]
	s_setprio 0
	s_setprio 1
	v_mfma_f32_16x16x32_f16 v[36:39], v[156:159], v[172:175], v[36:39]
	v_mfma_f32_16x16x32_f16 v[36:39], v[160:163], v[176:179], v[36:39]
	v_mfma_f32_16x16x32_f16 v[40:43], v[168:171], v[176:179], v[40:43]
	v_mfma_f32_16x16x32_f16 v[40:43], v[164:167], v[172:175], v[40:43]
	v_mfma_f32_16x16x32_f16 v[48:51], v[164:167], v[180:183], v[48:51]
	v_mfma_f32_16x16x32_f16 v[48:51], v[168:171], v[184:187], v[48:51]
	v_mfma_f32_16x16x32_f16 v[44:47], v[160:163], v[184:187], v[44:47]
	v_mfma_f32_16x16x32_f16 v[44:47], v[156:159], v[180:183], v[44:47]
	v_mfma_f32_16x16x32_f16 v[52:55], v[156:159], v[188:191], v[52:55]
	v_mfma_f32_16x16x32_f16 v[52:55], v[160:163], v[192:195], v[52:55]
	v_mfma_f32_16x16x32_f16 v[56:59], v[168:171], v[192:195], v[56:59]
	v_mfma_f32_16x16x32_f16 v[56:59], v[164:167], v[188:191], v[56:59]
	v_mfma_f32_16x16x32_f16 v[64:67], v[164:167], v[196:199], v[64:67]
	v_mfma_f32_16x16x32_f16 v[64:67], v[168:171], v[200:203], v[64:67]
	s_setprio 2
	s_barrier
	v_mfma_f32_16x16x32_f16 v[60:63], v[160:163], v[200:203], v[60:63]
	v_mfma_f32_16x16x32_f16 v[60:63], v[156:159], v[196:199], v[60:63]
	s_setprio 0
	s_add_i32 s16, s29, s38
	s_mov_b32 m0, s16
	ds_read_b128 v[172:175], v146 offset:49152
	ds_read_b128 v[176:179], v146 offset:50176
	ds_read_b128 v[180:183], v146 offset:51200
	ds_read_b128 v[184:187], v146 offset:52224
	ds_read_b128 v[188:191], v146 offset:53248
	ds_read_b128 v[192:195], v146 offset:54272
	ds_read_b128 v[196:199], v146 offset:55296
	ds_read_b128 v[200:203], v146 offset:56320
	global_load_lds_dwordx4 v136, s[88:89]
	s_add_i32 m0, s16, 0x2000
	s_add_u32 s6, s6, 0x80080
	s_addc_u32 s7, s7, 0
	s_add_i32 s16, s40, s38
	global_load_lds_dwordx4 v134, s[88:89]
	s_mov_b32 m0, s16
	s_nop 0
	global_load_lds_dwordx4 v136, s[6:7]
	s_add_i32 m0, s16, 0x2000
	s_nop 0
	global_load_lds_dwordx4 v134, s[6:7]
	s_mov_b32 m0, s64
	s_nop 0
	global_load_lds_dwordx4 v2, s[90:91]
	s_mov_b32 m0, s65
	s_nop 0
	global_load_lds_dwordx4 v132, s[90:91]
	s_waitcnt vmcnt(8)
	s_waitcnt lgkmcnt(0)
	s_barrier
	s_setprio 1
	s_waitcnt lgkmcnt(0)
	v_mfma_f32_16x16x32_f16 v[68:71], v[138:141], v[172:175], v[68:71]
	v_mfma_f32_16x16x32_f16 v[68:71], v[142:145], v[176:179], v[68:71]
	v_mfma_f32_16x16x32_f16 v[72:75], v[152:155], v[176:179], v[72:75]
	v_mfma_f32_16x16x32_f16 v[72:75], v[148:151], v[172:175], v[72:75]
	v_mfma_f32_16x16x32_f16 v[80:83], v[148:151], v[180:183], v[80:83]
	v_mfma_f32_16x16x32_f16 v[80:83], v[152:155], v[184:187], v[80:83]
	v_mfma_f32_16x16x32_f16 v[76:79], v[142:145], v[184:187], v[76:79]
	v_mfma_f32_16x16x32_f16 v[76:79], v[138:141], v[180:183], v[76:79]
	v_mfma_f32_16x16x32_f16 v[84:87], v[138:141], v[188:191], v[84:87]
	v_mfma_f32_16x16x32_f16 v[84:87], v[142:145], v[192:195], v[84:87]
	v_mfma_f32_16x16x32_f16 v[88:91], v[152:155], v[192:195], v[88:91]
	v_mfma_f32_16x16x32_f16 v[88:91], v[148:151], v[188:191], v[88:91]
	v_mfma_f32_16x16x32_f16 v[96:99], v[148:151], v[196:199], v[96:99]
	v_mfma_f32_16x16x32_f16 v[96:99], v[152:155], v[200:203], v[96:99]
	v_mfma_f32_16x16x32_f16 v[92:95], v[142:145], v[200:203], v[92:95]
	v_mfma_f32_16x16x32_f16 v[92:95], v[138:141], v[196:199], v[92:95]
	s_setprio 0
	s_setprio 1
	v_mfma_f32_16x16x32_f16 v[100:103], v[156:159], v[172:175], v[100:103]
	v_mfma_f32_16x16x32_f16 v[100:103], v[160:163], v[176:179], v[100:103]
	v_mfma_f32_16x16x32_f16 v[104:107], v[168:171], v[176:179], v[104:107]
	v_mfma_f32_16x16x32_f16 v[104:107], v[164:167], v[172:175], v[104:107]
	v_mfma_f32_16x16x32_f16 v[112:115], v[164:167], v[180:183], v[112:115]
	v_mfma_f32_16x16x32_f16 v[112:115], v[168:171], v[184:187], v[112:115]
	v_mfma_f32_16x16x32_f16 v[108:111], v[160:163], v[184:187], v[108:111]
	v_mfma_f32_16x16x32_f16 v[108:111], v[156:159], v[180:183], v[108:111]
	v_mfma_f32_16x16x32_f16 v[116:119], v[156:159], v[188:191], v[116:119]
	v_mfma_f32_16x16x32_f16 v[116:119], v[160:163], v[192:195], v[116:119]
	v_mfma_f32_16x16x32_f16 v[120:123], v[168:171], v[192:195], v[120:123]
	v_mfma_f32_16x16x32_f16 v[120:123], v[164:167], v[188:191], v[120:123]
	v_mfma_f32_16x16x32_f16 v[128:131], v[164:167], v[196:199], v[128:131]
	v_mfma_f32_16x16x32_f16 v[128:131], v[168:171], v[200:203], v[128:131]
	s_setprio 2
	s_barrier
	v_mfma_f32_16x16x32_f16 v[124:127], v[160:163], v[200:203], v[124:127]
	v_mfma_f32_16x16x32_f16 v[124:127], v[156:159], v[196:199], v[124:127]
	s_setprio 0
	s_add_i32 s28, s28, 2
	s_add_u32 s8, s8, 0x100
	s_addc_u32 s9, s9, 0
	s_add_u32 s26, s26, 0x100
	s_addc_u32 s27, s27, 0
	s_cmp_gt_u32 s28, 29
	s_cbranch_scc0 .LBB0_532
	s_and_b64 vcc, exec, s[50:51]
	s_cbranch_vccz .LBB0_535
.LBB0_535:
	v_cndmask_b32_e64 v135, 0, 1, s[10:11]
	v_cmp_ne_u32_e64 s[40:41], 1, v135
	s_andn2_b64 vcc, exec, s[10:11]
	s_cbranch_vccnz .LBB0_537
	s_add_u32 s6, s12, 0x80080
	s_addc_u32 s7, s13, 0
	s_mov_b32 m0, s66
	v_lshl_add_u64 v[140:141], s[6:7], 0, v[2:3]
	v_lshl_add_u64 v[138:139], s[6:7], 0, v[132:133]
	global_load_lds_dwordx4 v[140:141], off
	s_mov_b32 m0, s67
	s_nop 0
	global_load_lds_dwordx4 v[138:139], off

.LBB0_569:
	s_waitcnt lgkmcnt(0)
	v_mul_f32_e32 v140, 0xbfb8aa3b, v135
	v_pk_mul_f32 v[144:145], v[92:93], v[140:141] op_sel_hi:[1,0]
	v_mul_f32_e32 v142, v135, v135
	v_exp_f32_e32 v144, v144
	v_exp_f32_e32 v145, v145
	v_pk_mul_f32 v[150:151], v[92:93], v[124:125]
	v_pk_mul_f32 v[148:149], v[94:95], v[126:127]
	v_add_co_u32_e32 v138, vcc, 0x1e4000, v138
	v_pk_add_f32 v[144:145], v[144:145], 1.0 op_sel_hi:[1,0]
	s_nop 0
	v_addc_co_u32_e32 v139, vcc, 0, v139, vcc
	v_rcp_f32_e32 v144, v144
	v_rcp_f32_e32 v145, v145
	v_pk_mul_f32 v[152:153], v[98:99], v[130:131]
	v_pk_mul_f32 v[154:155], v[96:97], v[128:129]
	s_mov_b64 s[6:7], -1
	v_pk_mul_f32 v[144:145], v[142:143], v[144:145] op_sel_hi:[0,1]
	v_pk_mul_f32 v[144:145], v[150:151], v[144:145]
	v_pk_mul_f32 v[150:151], v[94:95], v[140:141] op_sel_hi:[1,0]
	s_and_b64 vcc, exec, s[40:41]
	v_exp_f32_e32 v150, v150
	v_exp_f32_e32 v151, v151
	s_nop 0
	v_pk_add_f32 v[150:151], v[150:151], 1.0 op_sel_hi:[1,0]
	s_nop 0
	v_rcp_f32_e32 v150, v150
	v_rcp_f32_e32 v151, v151
	s_nop 0
	v_pk_mul_f32 v[150:151], v[142:143], v[150:151] op_sel_hi:[0,1]
	v_pk_mul_f32 v[148:149], v[148:149], v[150:151]
	v_pk_mul_f32 v[150:151], v[96:97], v[140:141] op_sel_hi:[1,0]
	v_pk_mul_f32 v[140:141], v[98:99], v[140:141] op_sel_hi:[1,0]
	v_exp_f32_e32 v150, v150
	v_exp_f32_e32 v151, v151
	v_exp_f32_e32 v140, v140
	v_exp_f32_e32 v141, v141
	v_pk_add_f32 v[150:151], v[150:151], 1.0 op_sel_hi:[1,0]
	s_nop 0
	v_rcp_f32_e32 v150, v150
	v_pk_add_f32 v[140:141], v[140:141], 1.0 op_sel_hi:[1,0]
	v_rcp_f32_e32 v151, v151
	v_rcp_f32_e32 v140, v140
	v_rcp_f32_e32 v141, v141
	v_pk_mul_f32 v[150:151], v[142:143], v[150:151] op_sel_hi:[0,1]
	v_pk_mul_f32 v[150:151], v[154:155], v[150:151]
	v_pk_mul_f32 v[140:141], v[142:143], v[140:141] op_sel_hi:[0,1]
	v_pk_mul_f32 v[152:153], v[152:153], v[140:141]
	v_cvt_pk_bf16_f32 v140, v144, v145
	v_cvt_pk_bf16_f32 v141, v148, v149
	v_cvt_pk_bf16_f32 v142, v150, v151
	s_nop 0
	v_cvt_pk_bf16_f32 v143, v152, v153
	global_store_dwordx4 v[138:139], v[140:143], off
	s_cbranch_vccnz .LBB0_523
	s_andn2_b64 vcc, exec, s[46:47]
	s_cbranch_vccnz .LBB0_522
	s_branch .LBB0_522
.LBB0_572:
	s_waitcnt vmcnt(0)
	s_and_b64 vcc, exec, s[50:51]
	s_cbranch_vccz .Lgu_ue_skip
	s_barrier
.Lgu_ue_skip:
	s_barrier
